# ps1 + static s_setprio 2 for the four loader waves of the sample diff unit (compute waves stay at 0)
# baseline (speedup 1.0000x reference)
;     ...
;         typedef unsigned u32x2_t __attribute__((ext_vector_type(2)));
;         const int lt = tid - 256;
;         const int key0 = lt >> 5, q16 = lt & 31, cch = q16 >> 1, hlf = q16 & 1;
;         const char* kg = (const char*)(C.cdk + ((size_t)b * PAST * 4 + h) * 128) + (size_t)key0 * 2048 + q16 * 16;
;         const char* vg = (const char*)(C.cdv + ((size_t)b * PAST * 4 + h) * 128) + (size_t)key0 * 2048 + q16 * 16;
;         const int kd0 = (cch >> 3) * 8192 + (cch & 7) * 1024 + ((key0 ^ (cch & 7)) & 63) * 16 + hlf * 8;
;         const int vd0 = S2_V + (cch >> 2) * 4096 + key0 * 64 + (cch & 3) * 16 + hlf * 8;
;         v4u kA[8], vA[8], kB[8], vB[8];
;     ...
;         S2LOAD(kA, vA, 0); S2LOAD(kB, vB, 1);
; template <int KIND>
; __device__ __forceinline__ void attn_queue(const AttnCtx& C, unsigned* head, int nunits, LAS unsigned char* lds) {
;     ...
;         __syncthreads();
;         if (threadIdx.x == 0) slot[0] = __hip_atomic_fetch_add(head, 1u, __ATOMIC_RELAXED, __HIP_MEMORY_SCOPE_AGENT);
;         __syncthreads();
;         const unsigned u = slot[0];
;         if (u >= (unsigned)nunits) break;
.LBB0_299:
	s_or_b64 exec, exec, s[2:3]
	s_waitcnt lgkmcnt(0)
	s_barrier
	ds_read_b32 v2, v205
	s_movk_i32 s2, 0x7f
	s_waitcnt lgkmcnt(0)
	v_cmp_lt_u32_e32 vcc, s2, v2
	s_mov_b64 s[2:3], -1
	s_cbranch_vccnz .LBB0_294
	v_mov_b32_e32 v140, v0
	v_and_b32_e32 v142, 3, v2
	v_readfirstlane_b32 s5, v140
	s_ashr_i32 s4, s5, 6
	s_cmp_lt_i32 s4, 4
	v_and_b32_e32 v208, 31, v140
	v_lshrrev_b32_e32 v207, 2, v2
	s_cselect_b64 s[10:11], -1, 0
	s_cmp_gt_i32 s4, 3
	v_lshlrev_b32_e32 v206, 7, v142
	v_lshlrev_b32_e32 v141, 3, v140
	s_barrier
	s_cbranch_scc0 .LBB0_304
	s_setprio 2
	v_add_u32_e32 v143, 0xffffff00, v140
	v_lshlrev_b32_e32 v3, 21, v207
	v_ashrrev_i32_e32 v2, 5, v143
	v_or_b32_e32 v200, v3, v206
	v_readlane_b32 s60, v253, 7
	v_lshlrev_b64 v[130:131], 2, v[200:201]
	v_readlane_b32 s70, v253, 17
	v_readlane_b32 s71, v253, 18
	v_ashrrev_i32_e32 v3, 31, v2
	v_lshlrev_b64 v[132:133], 11, v[2:3]
	v_lshl_add_u64 v[4:5], s[70:71], 0, v[130:131]
	v_lshl_add_u64 v[4:5], v[4:5], 0, v[132:133]
	v_lshlrev_b32_e32 v200, 4, v208
	v_lshl_add_u64 v[134:135], v[4:5], 0, v[200:201]
	v_readlane_b32 s72, v253, 19
	v_readlane_b32 s73, v253, 20
	v_bfe_u32 v37, v208, 1, 3
	v_add_co_u32_e32 v6, vcc, s1, v134
	v_lshl_add_u64 v[4:5], s[72:73], 0, v[130:131]
	v_bitop3_b32 v3, v2, v37, 63 bitop3:0x6c
	v_addc_co_u32_e32 v7, vcc, 0, v135, vcc
	v_lshl_add_u64 v[34:35], v[4:5], 0, v[132:133]
	v_lshlrev_b32_e32 v66, 4, v3
	v_lshlrev_b32_e32 v146, 6, v2
	global_load_dwordx4 v[2:5], v[134:135], off nt
	global_load_dwordx4 v[10:13], v[6:7], off nt
	v_add_co_u32_e32 v6, vcc, s16, v134
	s_mov_b32 s2, 0x18000
	s_nop 0
	v_addc_co_u32_e32 v7, vcc, 0, v135, vcc
	v_add_co_u32_e32 v14, vcc, s17, v134
	global_load_dwordx4 v[6:9], v[6:7], off nt
	s_nop 0
	v_addc_co_u32_e32 v15, vcc, 0, v135, vcc
	global_load_dwordx4 v[18:21], v[14:15], off nt
	v_add_co_u32_e32 v14, vcc, s18, v134
	v_lshlrev_b32_e32 v38, 3, v208
	s_nop 0
	v_addc_co_u32_e32 v15, vcc, 0, v135, vcc
	v_add_co_u32_e32 v22, vcc, s19, v134
	v_lshl_add_u64 v[136:137], v[34:35], 0, v[200:201]
	s_nop 0
	v_addc_co_u32_e32 v23, vcc, 0, v135, vcc
	v_add_co_u32_e32 v26, vcc, s2, v134
	v_and_b32_e32 v148, 48, v38
	s_nop 0
	v_addc_co_u32_e32 v27, vcc, 0, v135, vcc
	v_add_co_u32_e32 v30, vcc, s20, v134
	global_load_dwordx4 v[14:17], v[14:15], off nt
	s_nop 0
	v_addc_co_u32_e32 v31, vcc, 0, v135, vcc
	v_add_co_u32_e32 v38, vcc, s1, v136
	global_load_dwordx4 v[22:25], v[22:23], off nt
	s_nop 0
	v_addc_co_u32_e32 v39, vcc, 0, v137, vcc
	v_add_co_u32_e32 v42, vcc, s16, v136
	global_load_dwordx4 v[26:29], v[26:27], off nt
	s_nop 0
	v_addc_co_u32_e32 v43, vcc, 0, v137, vcc
	v_add_co_u32_e32 v46, vcc, s17, v136
	global_load_dwordx4 v[30:33], v[30:31], off nt
	s_nop 0
	v_addc_co_u32_e32 v47, vcc, 0, v137, vcc
	v_add_co_u32_e32 v50, vcc, s18, v136
	v_lshlrev_b32_e32 v36, 9, v208
	s_nop 0
	v_addc_co_u32_e32 v51, vcc, 0, v137, vcc
	v_add_co_u32_e32 v54, vcc, s19, v136
	v_and_b32_e32 v34, 0x2000, v36
	s_nop 0
	v_addc_co_u32_e32 v55, vcc, 0, v137, vcc
	v_add_co_u32_e32 v58, vcc, s2, v136
	v_and_b32_e32 v145, 0x3000, v36
	v_lshl_or_b32 v67, v37, 10, v34
	global_load_dwordx4 v[34:37], v[136:137], off nt
	v_addc_co_u32_e32 v59, vcc, 0, v137, vcc
	global_load_dwordx4 v[38:41], v[38:39], off nt
	v_add_co_u32_e32 v62, vcc, s20, v136
	global_load_dwordx4 v[42:45], v[42:43], off nt
	v_readlane_b32 s12, v252, 18
	global_load_dwordx4 v[46:49], v[46:47], off nt
	v_and_b32_e32 v144, 8, v141
	global_load_dwordx4 v[50:53], v[50:51], off nt
	v_addc_co_u32_e32 v63, vcc, 0, v137, vcc
	global_load_dwordx4 v[54:57], v[54:55], off nt
	v_readlane_b32 s15, v252, 21
	global_load_dwordx4 v[58:61], v[58:59], off nt
	v_or3_b32 v147, v67, v66, v144
	global_load_dwordx4 v[62:65], v[62:63], off nt
	v_add_co_u32_e32 v66, vcc, s15, v134
	v_add_u32_e32 v138, 0, v147
	s_nop 0
	v_addc_co_u32_e32 v67, vcc, 0, v135, vcc
	v_add_co_u32_e32 v70, vcc, s21, v134
	global_load_dwordx4 v[66:69], v[66:67], off nt
	s_nop 0
	v_addc_co_u32_e32 v71, vcc, 0, v135, vcc
	global_load_dwordx4 v[74:77], v[70:71], off nt
	v_add_co_u32_e32 v70, vcc, s22, v134
	s_waitcnt vmcnt(17)
	v_cvt_pk_bf16_f32 v2, v2, v3
	v_addc_co_u32_e32 v71, vcc, 0, v135, vcc
	v_add_co_u32_e32 v78, vcc, s23, v134
	global_load_dwordx4 v[70:73], v[70:71], off nt
	s_nop 0
	v_addc_co_u32_e32 v79, vcc, 0, v135, vcc
	v_add_co_u32_e32 v82, vcc, s24, v134
	global_load_dwordx4 v[78:81], v[78:79], off nt
	s_nop 0
	v_addc_co_u32_e32 v83, vcc, 0, v135, vcc
	v_add_co_u32_e32 v86, vcc, s25, v134
	global_load_dwordx4 v[82:85], v[82:83], off nt
	s_nop 0
	v_addc_co_u32_e32 v87, vcc, 0, v135, vcc
	v_add_co_u32_e32 v90, vcc, s26, v134
	global_load_dwordx4 v[86:89], v[86:87], off nt
	s_nop 0
	v_addc_co_u32_e32 v91, vcc, 0, v135, vcc
	v_add_co_u32_e32 v94, vcc, s27, v134
	global_load_dwordx4 v[90:93], v[90:91], off nt
	s_nop 0
	v_addc_co_u32_e32 v95, vcc, 0, v135, vcc
	v_add_co_u32_e32 v98, vcc, s15, v136
	global_load_dwordx4 v[94:97], v[94:95], off nt
	s_nop 0
	v_addc_co_u32_e32 v99, vcc, 0, v137, vcc
	v_add_co_u32_e32 v102, vcc, s21, v136
	global_load_dwordx4 v[98:101], v[98:99], off nt
	s_nop 0
	v_addc_co_u32_e32 v103, vcc, 0, v137, vcc
	v_add_co_u32_e32 v106, vcc, s22, v136
	global_load_dwordx4 v[102:105], v[102:103], off nt
	s_nop 0
	v_addc_co_u32_e32 v107, vcc, 0, v137, vcc
	v_add_co_u32_e32 v110, vcc, s23, v136
	global_load_dwordx4 v[106:109], v[106:107], off nt
	s_nop 0
	v_addc_co_u32_e32 v111, vcc, 0, v137, vcc
	v_add_co_u32_e32 v114, vcc, s24, v136
	global_load_dwordx4 v[110:113], v[110:111], off nt
	s_nop 0
	v_addc_co_u32_e32 v115, vcc, 0, v137, vcc
	v_add_co_u32_e32 v118, vcc, s25, v136
	global_load_dwordx4 v[114:117], v[114:115], off nt
	s_nop 0
	v_addc_co_u32_e32 v119, vcc, 0, v137, vcc
	v_add_co_u32_e32 v122, vcc, s26, v136
	global_load_dwordx4 v[118:121], v[118:119], off nt
	s_nop 0
	v_addc_co_u32_e32 v123, vcc, 0, v137, vcc
	v_add_co_u32_e32 v126, vcc, s27, v136
	global_load_dwordx4 v[122:125], v[122:123], off nt
	s_nop 0
	v_addc_co_u32_e32 v127, vcc, 0, v137, vcc
	global_load_dwordx4 v[126:129], v[126:127], off nt
	v_cvt_pk_bf16_f32 v3, v4, v5
	s_waitcnt vmcnt(30)
;     ...
;         S2LOAD(kA, vA, 0); S2LOAD(kB, vB, 1);
;         S2WRITE(kA, vA, 0); S2LOAD(kA, vA, 2);
;         S2WRITE(kB, vB, 1); S2LOAD(kB, vB, 3);
	v_cvt_pk_bf16_f32 v4, v10, v11
	v_cvt_pk_bf16_f32 v5, v12, v13
	ds_write2_b64 v138, v[2:3], v[4:5] offset1:16
	s_waitcnt vmcnt(29)
	v_cvt_pk_bf16_f32 v2, v6, v7
	v_cvt_pk_bf16_f32 v3, v8, v9
	s_waitcnt vmcnt(28)
	v_cvt_pk_bf16_f32 v4, v18, v19
	v_cvt_pk_bf16_f32 v5, v20, v21
	ds_write2_b64 v138, v[2:3], v[4:5] offset0:32 offset1:48
	s_waitcnt vmcnt(27)
	v_cvt_pk_bf16_f32 v2, v14, v15
	v_cvt_pk_bf16_f32 v3, v16, v17
	s_waitcnt vmcnt(26)
	v_cvt_pk_bf16_f32 v4, v22, v23
	v_cvt_pk_bf16_f32 v5, v24, v25
	ds_write2_b64 v138, v[2:3], v[4:5] offset0:64 offset1:80
	s_waitcnt vmcnt(25)
	v_cvt_pk_bf16_f32 v2, v26, v27
	v_cvt_pk_bf16_f32 v3, v28, v29
	s_waitcnt vmcnt(24)
	v_cvt_pk_bf16_f32 v4, v30, v31
	v_cvt_pk_bf16_f32 v5, v32, v33
	ds_write2_b64 v138, v[2:3], v[4:5] offset0:96 offset1:112
	v_or_b32_e32 v2, v144, v146
	v_add_u32_e32 v2, v2, v145
	v_or_b32_e32 v149, v2, v148
	v_add_u32_e32 v139, 0, v149
	s_waitcnt vmcnt(23)
	v_cvt_pk_bf16_f32 v2, v34, v35
	v_cvt_pk_bf16_f32 v3, v36, v37
	s_waitcnt vmcnt(22)
	v_cvt_pk_bf16_f32 v4, v38, v39
	v_cvt_pk_bf16_f32 v5, v40, v41
	ds_write2st64_b64 v139, v[2:3], v[4:5] offset0:32 offset1:33
	s_waitcnt vmcnt(21)
	v_cvt_pk_bf16_f32 v2, v42, v43
	v_cvt_pk_bf16_f32 v3, v44, v45
	s_waitcnt vmcnt(20)
	v_cvt_pk_bf16_f32 v4, v46, v47
	v_cvt_pk_bf16_f32 v5, v48, v49
	ds_write2st64_b64 v139, v[2:3], v[4:5] offset0:34 offset1:35
	s_waitcnt vmcnt(19)
	v_cvt_pk_bf16_f32 v2, v50, v51
	v_cvt_pk_bf16_f32 v3, v52, v53
	s_waitcnt vmcnt(18)
	v_cvt_pk_bf16_f32 v4, v54, v55
	v_cvt_pk_bf16_f32 v5, v56, v57
	ds_write2st64_b64 v139, v[2:3], v[4:5] offset0:36 offset1:37
	s_waitcnt vmcnt(17)
	v_cvt_pk_bf16_f32 v2, v58, v59
	v_cvt_pk_bf16_f32 v3, v60, v61
	s_waitcnt vmcnt(16)
	v_cvt_pk_bf16_f32 v4, v62, v63
	v_cvt_pk_bf16_f32 v5, v64, v65
	ds_write2st64_b64 v139, v[2:3], v[4:5] offset0:38 offset1:39
	v_add_co_u32_e32 v2, vcc, s28, v134
	s_waitcnt vmcnt(15)
	v_cvt_pk_bf16_f32 v66, v66, v67
	v_addc_co_u32_e32 v3, vcc, 0, v135, vcc
	v_add_co_u32_e32 v6, vcc, s29, v134
	global_load_dwordx4 v[2:5], v[2:3], off nt
	s_nop 0
	v_addc_co_u32_e32 v7, vcc, 0, v135, vcc
	global_load_dwordx4 v[22:25], v[6:7], off nt
	v_add_co_u32_e32 v6, vcc, s30, v134
	v_cvt_pk_bf16_f32 v67, v68, v69
	s_nop 0
	v_addc_co_u32_e32 v7, vcc, 0, v135, vcc
	v_add_co_u32_e32 v10, vcc, s31, v134
	global_load_dwordx4 v[6:9], v[6:7], off nt
	s_nop 0
	v_addc_co_u32_e32 v11, vcc, 0, v135, vcc
	global_load_dwordx4 v[26:29], v[10:11], off nt
	v_add_co_u32_e32 v10, vcc, s33, v134
	s_waitcnt vmcnt(18)
	v_cvt_pk_bf16_f32 v68, v74, v75
	v_addc_co_u32_e32 v11, vcc, 0, v135, vcc
	v_add_co_u32_e32 v14, vcc, s34, v134
	global_load_dwordx4 v[10:13], v[10:11], off nt
	s_nop 0
	v_addc_co_u32_e32 v15, vcc, 0, v135, vcc
	global_load_dwordx4 v[30:33], v[14:15], off nt
	v_add_co_u32_e32 v14, vcc, s35, v134
	v_cvt_pk_bf16_f32 v69, v76, v77
	s_nop 0
	v_addc_co_u32_e32 v15, vcc, 0, v135, vcc
	v_add_co_u32_e32 v18, vcc, s36, v134
	v_add_u32_e32 v74, 0x8000, v138
	s_nop 0
	v_addc_co_u32_e32 v19, vcc, 0, v135, vcc
	v_add_co_u32_e32 v34, vcc, s28, v136
	ds_write2_b64 v74, v[66:67], v[68:69] offset1:16
	s_nop 0
	v_addc_co_u32_e32 v35, vcc, 0, v137, vcc
	global_load_dwordx4 v[42:45], v[34:35], off nt
	v_add_co_u32_e32 v34, vcc, s29, v136
	s_waitcnt vmcnt(20)
	v_cvt_pk_bf16_f32 v66, v70, v71
	v_addc_co_u32_e32 v35, vcc, 0, v137, vcc
	global_load_dwordx4 v[58:61], v[34:35], off nt
	v_add_co_u32_e32 v34, vcc, s30, v136
	v_cvt_pk_bf16_f32 v67, v72, v73
	s_nop 0
	v_addc_co_u32_e32 v35, vcc, 0, v137, vcc
	global_load_dwordx4 v[38:41], v[34:35], off nt
	v_add_co_u32_e32 v34, vcc, s31, v136
	s_waitcnt vmcnt(21)
	v_cvt_pk_bf16_f32 v68, v78, v79
	v_addc_co_u32_e32 v35, vcc, 0, v137, vcc
	global_load_dwordx4 v[54:57], v[34:35], off nt
	v_add_co_u32_e32 v34, vcc, s33, v136
	v_cvt_pk_bf16_f32 v69, v80, v81
	s_nop 0
	v_addc_co_u32_e32 v35, vcc, 0, v137, vcc
	global_load_dwordx4 v[46:49], v[34:35], off nt
	v_add_co_u32_e32 v34, vcc, s34, v136
	ds_write2_b64 v74, v[66:67], v[68:69] offset0:32 offset1:48
	s_waitcnt vmcnt(22)
	v_cvt_pk_bf16_f32 v66, v82, v83
	v_cvt_pk_bf16_f32 v67, v84, v85
	s_waitcnt vmcnt(21)
	v_cvt_pk_bf16_f32 v68, v86, v87
	v_cvt_pk_bf16_f32 v69, v88, v89
	v_addc_co_u32_e32 v35, vcc, 0, v137, vcc
	ds_write2_b64 v74, v[66:67], v[68:69] offset0:64 offset1:80
	s_waitcnt vmcnt(20)
	v_cvt_pk_bf16_f32 v66, v90, v91
	v_cvt_pk_bf16_f32 v67, v92, v93
	s_waitcnt vmcnt(19)
; #define S2BAR() asm volatile("s_waitcnt lgkmcnt(0)\n\ts_barrier" ::: "memory")
;     ...
;         S2LOAD(kA, vA, 0); S2LOAD(kB, vB, 1);
;         S2WRITE(kA, vA, 0); S2LOAD(kA, vA, 2);
;         S2WRITE(kB, vB, 1); S2LOAD(kB, vB, 3);
;         S2BAR();
	v_cvt_pk_bf16_f32 v68, v94, v95
	v_cvt_pk_bf16_f32 v69, v96, v97
	global_load_dwordx4 v[62:65], v[34:35], off nt
	v_add_co_u32_e32 v34, vcc, s35, v136
	ds_write2_b64 v74, v[66:67], v[68:69] offset0:96 offset1:112
	s_waitcnt vmcnt(19)
	v_cvt_pk_bf16_f32 v66, v98, v99
	v_cvt_pk_bf16_f32 v67, v100, v101
	s_waitcnt vmcnt(18)
	v_cvt_pk_bf16_f32 v68, v102, v103
	v_cvt_pk_bf16_f32 v69, v104, v105
	v_addc_co_u32_e32 v35, vcc, 0, v137, vcc
	ds_write2st64_b64 v139, v[66:67], v[68:69] offset0:96 offset1:97
	s_waitcnt vmcnt(17)
	v_cvt_pk_bf16_f32 v66, v106, v107
	v_cvt_pk_bf16_f32 v67, v108, v109
	s_waitcnt vmcnt(16)
	v_cvt_pk_bf16_f32 v68, v110, v111
	v_cvt_pk_bf16_f32 v69, v112, v113
	global_load_dwordx4 v[50:53], v[34:35], off nt
	v_add_co_u32_e32 v34, vcc, s36, v136
	ds_write2st64_b64 v139, v[66:67], v[68:69] offset0:98 offset1:99
	s_waitcnt vmcnt(16)
	v_cvt_pk_bf16_f32 v66, v114, v115
	v_cvt_pk_bf16_f32 v67, v116, v117
	s_waitcnt vmcnt(15)
	v_cvt_pk_bf16_f32 v68, v118, v119
	v_cvt_pk_bf16_f32 v69, v120, v121
	v_addc_co_u32_e32 v35, vcc, 0, v137, vcc
	ds_write2st64_b64 v139, v[66:67], v[68:69] offset0:100 offset1:101
	s_waitcnt vmcnt(14)
	v_cvt_pk_bf16_f32 v66, v122, v123
	v_cvt_pk_bf16_f32 v67, v124, v125
	s_waitcnt vmcnt(13)
	v_cvt_pk_bf16_f32 v68, v126, v127
	v_cvt_pk_bf16_f32 v69, v128, v129
	ds_write2st64_b64 v139, v[66:67], v[68:69] offset0:102 offset1:103
	v_add_co_u32_e32 v66, vcc, s37, v134
	s_mov_b32 s3, 0x78000
	s_nop 0
	v_addc_co_u32_e32 v67, vcc, 0, v135, vcc
	global_load_dwordx4 v[74:77], v[66:67], off nt
	v_add_co_u32_e32 v66, vcc, s38, v134
	global_load_dwordx4 v[14:17], v[14:15], off nt
	s_nop 0
	v_addc_co_u32_e32 v67, vcc, 0, v135, vcc
	global_load_dwordx4 v[86:89], v[66:67], off nt
	v_add_co_u32_e32 v66, vcc, s39, v134
	global_load_dwordx4 v[18:21], v[18:19], off nt
	s_nop 0
	v_addc_co_u32_e32 v67, vcc, 0, v135, vcc
	global_load_dwordx4 v[70:73], v[66:67], off nt
	v_add_co_u32_e32 v66, vcc, s40, v134
	global_load_dwordx4 v[34:37], v[34:35], off nt
	s_nop 0
	v_addc_co_u32_e32 v67, vcc, 0, v135, vcc
	global_load_dwordx4 v[82:85], v[66:67], off nt
	v_add_co_u32_e32 v66, vcc, s41, v134
	v_or_b32_e32 v132, v132, v200
	s_nop 0
	v_addc_co_u32_e32 v67, vcc, 0, v135, vcc
	v_add_co_u32_e32 v78, vcc, s42, v134
	global_load_dwordx4 v[66:69], v[66:67], off nt
	s_nop 0
	v_addc_co_u32_e32 v79, vcc, 0, v135, vcc
	v_add_co_u32_e32 v90, vcc, s3, v134
	s_mov_b32 s3, 0x7c000
	s_nop 0
	v_addc_co_u32_e32 v91, vcc, 0, v135, vcc
	v_add_co_u32_e32 v94, vcc, s3, v134
	global_load_dwordx4 v[90:93], v[90:91], off nt
	s_nop 0
	v_addc_co_u32_e32 v95, vcc, 0, v135, vcc
	global_load_dwordx4 v[98:101], v[94:95], off nt
	v_add_co_u32_e32 v94, vcc, s37, v136
	global_load_dwordx4 v[78:81], v[78:79], off nt
	s_nop 0
	v_addc_co_u32_e32 v95, vcc, 0, v137, vcc
	v_add_co_u32_e32 v102, vcc, s38, v136
	global_load_dwordx4 v[94:97], v[94:95], off nt
	s_nop 0
	v_addc_co_u32_e32 v103, vcc, 0, v137, vcc
	global_load_dwordx4 v[106:109], v[102:103], off nt
	v_add_co_u32_e32 v102, vcc, s39, v136
	v_lshl_add_u64 v[134:135], s[70:71], 0, v[132:133]
	s_nop 0
	v_addc_co_u32_e32 v103, vcc, 0, v137, vcc
	v_add_co_u32_e32 v110, vcc, s40, v136
	global_load_dwordx4 v[102:105], v[102:103], off nt
	s_nop 0
	v_addc_co_u32_e32 v111, vcc, 0, v137, vcc
	v_add_co_u32_e32 v114, vcc, s41, v136
	global_load_dwordx4 v[110:113], v[110:111], off nt
	s_nop 0
	v_addc_co_u32_e32 v115, vcc, 0, v137, vcc
	v_add_co_u32_e32 v118, vcc, s42, v136
	global_load_dwordx4 v[114:117], v[114:115], off nt
	s_nop 0
	v_addc_co_u32_e32 v119, vcc, 0, v137, vcc
	v_add_co_u32_e32 v122, vcc, 0x78000, v136
	global_load_dwordx4 v[118:121], v[118:119], off nt
	s_nop 0
	v_addc_co_u32_e32 v123, vcc, 0, v137, vcc
	v_add_co_u32_e32 v126, vcc, 0x7c000, v136
	global_load_dwordx4 v[122:125], v[122:123], off nt
	s_nop 0
	v_addc_co_u32_e32 v127, vcc, 0, v137, vcc
	global_load_dwordx4 v[126:129], v[126:127], off nt
	s_waitcnt lgkmcnt(0)
	s_barrier
	v_lshl_add_u64 v[132:133], s[72:73], 0, v[132:133]
	s_mov_b32 s3, -2
	v_readlane_b32 s61, v253, 8
	v_readlane_b32 s62, v253, 9
	v_readlane_b32 s63, v253, 10
	v_readlane_b32 s64, v253, 11
	v_readlane_b32 s65, v253, 12
	v_readlane_b32 s66, v253, 13
	v_readlane_b32 s67, v253, 14
	v_readlane_b32 s68, v253, 15
	v_readlane_b32 s69, v253, 16
	v_readlane_b32 s74, v253, 21
	v_readlane_b32 s75, v253, 22
	v_readlane_b32 s13, v252, 19
	v_readlane_b32 s14, v252, 20

;     ...
;         const int qrow = NP + b * 64 + 32 * qblk + r32, qpos = PAST + 32 * qblk + r32;
;         const float c15 = tab[0];
;         const lcp qp0 = (lcp)(lds + S2_Q) + wid * 4096 + lane * 16;
;         {
;             bf16x8 qr[4]; const bf16* qsrc = C.DQ + (size_t)qrow * 512 + h * 128 + map * 64;
; #pragma unroll
;             for (int d0 = 0; d0 < 4; ++d0) qr[d0] = *(const bf16x8*)(qsrc + d0 * 16 + hi * 8);
; #pragma unroll
;             for (int d0 = 0; d0 < 4; ++d0) *(LAS bf16x8*)((LAS unsigned char*)qp0 + d0 * 1024) = qr[d0];
;         }
;     ...
;         unsigned ka0, ka1, ka2, ka3;
;         { const int c0 = hi, c1 = 2 + hi, c2 = 4 + hi, c3 = 6 + hi;
;           ka0 = map * 8192 + c0 * 1024 + ((r32 ^ c0) & 63) * 16; ka1 = map * 8192 + c1 * 1024 + ((r32 ^ c1) & 63) * 16;
;           ka2 = map * 8192 + c2 * 1024 + ((r32 ^ c2) & 63) * 16; ka3 = map * 8192 + c3 * 1024 + ((r32 ^ c3) & 63) * 16; }
;         const lcp vp0 = (lcp)(lds + S2_V) + ((lane >> 4) & 1) * 32 + (lane & 3) * 8 + (4 * hi + ((lane & 15) >> 2)) * 64;
;         bf16x8 kf[8];
;         float nm = c15;
; #pragma unroll
;         for (int d = 0; d < 4; ++d) o[d] = (f32x16){0.f,0.f,0.f,0.f,0.f,0.f,0.f,0.f,0.f,0.f,0.f,0.f,0.f,0.f,0.f,0.f};
;         bool resc = false;
;     ...
;         f32x16 pA0, pA1, pB0, pB1;
;         S2BAR();
;         {
;             INITC(pA0, pA1);
;             { const bf16x8 b0 = *(const LAS bf16x8*)(lds + ka0), b1 = *(const LAS bf16x8*)(lds + ka0 + 512); const bf16x8 qv = QRD(0);
;               pA0 = __builtin_amdgcn_mfma_f32_32x32x16_bf16(b0, qv, pA0, 0, 0, 0); pA1 = __builtin_amdgcn_mfma_f32_32x32x16_bf16(b1, qv, pA1, 0, 0, 0); }
;             { const bf16x8 b0 = *(const LAS bf16x8*)(lds + ka1), b1 = *(const LAS bf16x8*)(lds + ka1 + 512); const bf16x8 qv = QRD(1);
;               pA0 = __builtin_amdgcn_mfma_f32_32x32x16_bf16(b0, qv, pA0, 0, 0, 0); pA1 = __builtin_amdgcn_mfma_f32_32x32x16_bf16(b1, qv, pA1, 0, 0, 0); }
;             { const bf16x8 b0 = *(const LAS bf16x8*)(lds + ka2), b1 = *(const LAS bf16x8*)(lds + ka2 + 512); const bf16x8 qv = QRD(2);
;               pA0 = __builtin_amdgcn_mfma_f32_32x32x16_bf16(b0, qv, pA0, 0, 0, 0); pA1 = __builtin_amdgcn_mfma_f32_32x32x16_bf16(b1, qv, pA1, 0, 0, 0); }
;             { const bf16x8 b0 = *(const LAS bf16x8*)(lds + ka3), b1 = *(const LAS bf16x8*)(lds + ka3 + 512); const bf16x8 qv = QRD(3);
.LBB0_304:
	s_setprio 0
	s_bfe_u32 s61, s5, 0x10007
	s_and_b32 s5, s5, 0x3fffffc0
	s_lshl_b32 s5, s5, 2
	s_add_i32 s62, s5, 0
	v_bfe_u32 v209, v140, 5, 1
	s_and_b32 s60, s4, 1
	s_add_i32 s62, s62, 0x21c00
	s_and_b64 vcc, exec, s[2:3]
	v_lshlrev_b32_e32 v200, 8, v142
	s_cbranch_vccz .LBB0_348
	v_lshlrev_b32_e32 v2, 6, v207
	s_lshl_b32 s14, s60, 5
	v_or_b32_e32 v2, s14, v2
	v_or_b32_e32 v2, v2, v208
	v_readlane_b32 s2, v253, 54
	v_lshlrev_b32_e32 v2, 10, v2
	v_mov_b32_e32 v3, v201
	v_readlane_b32 s3, v253, 55
	s_lshl_b32 s6, s61, 7
	v_lshlrev_b32_e32 v202, 4, v209
	v_lshl_add_u64 v[2:3], s[2:3], 0, v[2:3]
	v_lshl_add_u64 v[2:3], v[2:3], 0, v[200:201]
	v_lshl_add_u64 v[2:3], v[2:3], 0, s[6:7]
	v_mov_b32_e32 v203, v201
	v_lshl_add_u64 v[2:3], v[2:3], 0, v[202:203]
	s_mov_b64 s[2:3], 0x1000000
	v_lshl_add_u64 v[14:15], v[2:3], 0, s[2:3]
	s_mov_b32 s2, 0x1000000
	v_add_co_u32_e32 v2, vcc, s2, v2
	s_movk_i32 s2, 0x300
	s_nop 0
	v_addc_co_u32_e32 v3, vcc, 0, v3, vcc
	global_load_dwordx4 v[2:5], v[2:3], off
	s_nop 0
	global_load_dwordx4 v[6:9], v[14:15], off offset:32
	global_load_dwordx4 v[10:13], v[14:15], off offset:64
	s_nop 0
	global_load_dwordx4 v[14:17], v[14:15], off offset:96
	v_mul_lo_u32 v18, v142, s2
	s_lshl_b32 s2, s4, 12
	v_and_b32_e32 v50, 63, v140
	s_add_i32 s2, s2, 0
	v_add_u32_e32 v18, 0, v18
	v_lshlrev_b32_e32 v21, 4, v50
	s_add_i32 s2, s2, 0x22800
	v_xor_b32_e32 v19, v209, v208
	v_add_u32_e32 v210, 0x20400, v18
	v_add_u32_e32 v212, s2, v21
	s_lshl_b32 s3, s61, 13
	v_lshl_add_u32 v20, v209, 10, 0
	ds_read_b32 v66, v210
	v_lshlrev_b32_e32 v18, 4, v19
	v_add3_u32 v211, v20, v18, s3
	v_mov_b32_e32 v51, v201
	v_mov_b32_e32 v52, v201
	s_waitcnt lgkmcnt(0)
	v_mov_b32_e32 v67, v66
	v_mov_b32_e32 v68, v66
	v_mov_b32_e32 v69, v66
	v_mov_b32_e32 v70, v66
	v_mov_b32_e32 v71, v66
	v_mov_b32_e32 v72, v66
	v_mov_b32_e32 v73, v66
	v_mov_b32_e32 v74, v66
	v_mov_b32_e32 v75, v66
	v_mov_b32_e32 v76, v66
	v_mov_b32_e32 v77, v66
	v_mov_b32_e32 v78, v66
	v_mov_b32_e32 v79, v66
	v_mov_b32_e32 v80, v66
	v_mov_b32_e32 v81, v66
	v_mov_b32_e32 v53, v201
	v_mov_b32_e32 v54, v201
	v_mov_b32_e32 v55, v201
	v_mov_b32_e32 v56, v201
	v_mov_b32_e32 v57, v201
	v_mov_b32_e32 v58, v201
	v_mov_b32_e32 v59, v201
	v_mov_b32_e32 v60, v201
	v_mov_b32_e32 v61, v201
	v_mov_b32_e32 v62, v201
	v_mov_b32_e32 v63, v201
	v_mov_b32_e32 v64, v201
	v_mov_b32_e32 v65, v201
	v_mov_b32_e32 v219, 0
	s_mov_b32 s6, -1
	s_mov_b32 s15, 0x20000
	s_waitcnt vmcnt(3)
	ds_write_b128 v212, v[2:5]
	s_waitcnt vmcnt(2)
	ds_write_b128 v212, v[6:9] offset:1024
	s_waitcnt vmcnt(1)
	ds_write_b128 v212, v[10:13] offset:2048
	s_waitcnt vmcnt(0)
	ds_write_b128 v212, v[14:17] offset:3072
	s_waitcnt lgkmcnt(0)
	s_barrier
	ds_read_b128 v[18:21], v211
	ds_read_b128 v[34:37], v212
	ds_read_b128 v[38:41], v211 offset:512
	ds_read_b128 v[42:45], v212 offset:1024
	s_waitcnt lgkmcnt(2)
	v_mfma_f32_32x32x16_bf16 v[2:17], v[18:21], v[34:37], v[66:81]
	v_or_b32_e32 v18, 2, v209
	v_bitop3_b32 v19, v209, v208, 2 bitop3:0x36
	v_lshlrev_b32_e32 v18, 10, v18
	v_lshl_add_u32 v19, v19, 4, 0
	v_add3_u32 v213, v19, v18, s3
	v_mov_b64_e32 v[18:19], v[66:67]
	v_mov_b64_e32 v[20:21], v[68:69]
	v_mov_b64_e32 v[22:23], v[70:71]
	v_mov_b64_e32 v[24:25], v[72:73]
	v_mov_b64_e32 v[26:27], v[74:75]
	v_mov_b64_e32 v[28:29], v[76:77]
	v_mov_b64_e32 v[30:31], v[78:79]
	v_mov_b64_e32 v[32:33], v[80:81]
	v_lshl_add_u32 v67, v208, 2, s62
	s_waitcnt lgkmcnt(1)
	v_mfma_f32_32x32x16_bf16 v[18:33], v[38:41], v[34:37], v[18:33]
	ds_read_b128 v[34:37], v213
	ds_read_b128 v[38:41], v213 offset:512
	s_waitcnt lgkmcnt(1)
	v_mfma_f32_32x32x16_bf16 v[2:17], v[34:37], v[42:45], v[2:17]
	v_or_b32_e32 v34, 4, v209
	v_bitop3_b32 v35, v209, v208, 4 bitop3:0x36
	v_lshlrev_b32_e32 v34, 10, v34
	v_lshl_add_u32 v35, v35, 4, 0
	v_add3_u32 v214, v35, v34, s3
	s_waitcnt lgkmcnt(0)
	v_mfma_f32_32x32x16_bf16 v[18:33], v[38:41], v[42:45], v[18:33]
	ds_read_b128 v[34:37], v214
	ds_read_b128 v[38:41], v212 offset:2048
	ds_read_b128 v[42:45], v214 offset:512
	ds_read_b128 v[46:49], v212 offset:3072
	s_waitcnt lgkmcnt(2)
	v_mfma_f32_32x32x16_bf16 v[2:17], v[34:37], v[38:41], v[2:17]
	v_or_b32_e32 v34, 6, v209
	v_bitop3_b32 v35, v209, v208, 6 bitop3:0x36
	v_lshlrev_b32_e32 v34, 10, v34
	v_lshl_add_u32 v35, v35, 4, 0
	v_add3_u32 v215, v35, v34, s3
	v_cmp_gt_u32_e64 s[2:3], 32, v50
	v_mov_b32_e32 v50, v201
	s_waitcnt lgkmcnt(1)
	v_mfma_f32_32x32x16_bf16 v[18:33], v[42:45], v[38:41], v[18:33]
	ds_read_b128 v[34:37], v215
	ds_read_b128 v[38:41], v215 offset:512
	ds_read_b128 v[192:195], v211 offset:32768
	ds_read_b128 v[184:187], v211 offset:33280
	ds_read_b128 v[188:191], v213 offset:32768
	ds_read_b128 v[180:183], v213 offset:33280
	ds_read_b128 v[176:179], v214 offset:32768
	ds_read_b128 v[172:175], v214 offset:33280
	ds_read_b128 v[168:171], v215 offset:32768
	ds_read_b128 v[164:167], v215 offset:33280
	s_waitcnt lgkmcnt(0)
	s_barrier
; #define TMX3(a, b, c) __builtin_fmaxf(__builtin_fmaxf((a), (b)), (c))
; #define TEX(v) __builtin_amdgcn_exp2f(v)
; #define S2BAR() asm volatile("s_waitcnt lgkmcnt(0)\n\ts_barrier" ::: "memory")
; #define KLD(j, KA, soff) do { kf[2 * (j)] = *(const LAS bf16x8*)(lds + (KA) + (soff)); kf[2 * (j) + 1] = *(const LAS bf16x8*)(lds + (KA) + (soff) + 512); } while (0)
;     ...
;             float rm = TMX3(pA0[0], pA0[1], pA1[0]);
; #pragma unroll
;             for (int r = 1; r < 16; ++r) rm = TMX3(rm, pA0[r], pA1[r]);
;             { auto rr = __builtin_amdgcn_permlane32_swap(__float_as_uint(rm), __float_as_uint(rm), false, false); rm = __builtin_fmaxf(__uint_as_float(rr[0]), __uint_as_float(rr[1])); }
;             nm -= rm;
; #pragma unroll
;             for (int r = 0; r < 16; ++r) { pA0[r] = TEX(pA0[r] - rm); pA1[r] = TEX(pA1[r] - rm); }
;         }
;         KLD(0, ka0, S2_SLOT); KLD(1, ka1, S2_SLOT); KLD(2, ka2, S2_SLOT); KLD(3, ka3, S2_SLOT);
;         S2BAR();
;         s16x4 vl0, vh0, vl1, vh1, vl2, vh2, vl3, vh3; v4u pw0, pw1, pw2, pw3;
;         bf16x8 qa = QRD(0), qb_;
	ds_read_b128 v[196:199], v212
	s_waitcnt lgkmcnt(10)
	v_mfma_f32_32x32x16_bf16 v[2:17], v[34:37], v[46:49], v[2:17]
	v_lshlrev_b32_e32 v34, 1, v140
	v_and_b32_e32 v35, 24, v141
	v_and_b32_e32 v34, 32, v34
	v_add3_u32 v34, 0, v34, v35
	v_lshlrev_b32_e32 v37, 4, v140
	v_lshlrev_b32_e32 v36, 8, v209
	v_and_b32_e32 v37, 0xc0, v37
	s_waitcnt lgkmcnt(9)
	v_mfma_f32_32x32x16_bf16 v[18:33], v[38:41], v[46:49], v[18:33]
	v_add3_u32 v203, v34, v36, v37
	s_nop 10
	v_max3_f32 v35, v2, v3, v18
	v_max3_f32 v35, v35, v3, v19
	v_max3_f32 v35, v35, v4, v20
	v_max3_f32 v35, v35, v5, v21
	v_max3_f32 v35, v35, v6, v22
	v_max3_f32 v35, v35, v7, v23
	v_max3_f32 v35, v35, v8, v24
	v_max3_f32 v35, v35, v9, v25
	v_max3_f32 v35, v35, v10, v26
	v_max3_f32 v35, v35, v11, v27
	v_max3_f32 v35, v35, v12, v28
	v_max3_f32 v35, v35, v13, v29
	v_max3_f32 v35, v35, v14, v30
	v_max3_f32 v35, v35, v15, v31
	v_max3_f32 v35, v35, v16, v32
	v_max3_f32 v35, v35, v17, v33
	v_mov_b32_e32 v38, v35
	s_nop 1
	v_permlane32_swap_b32_e32 v35, v38
	v_max_f32_e32 v38, v38, v38
	v_max_f32_e32 v35, v35, v35
	v_max_f32_e32 v35, v35, v38
	v_sub_f32_e32 v2, v2, v35
	v_exp_f32_e32 v100, v2
	v_sub_f32_e32 v2, v10, v35
	v_exp_f32_e32 v108, v2
	v_sub_f32_e32 v2, v26, v35
	v_exp_f32_e32 v92, v2
	v_sub_f32_e32 v2, v11, v35
	v_exp_f32_e32 v109, v2
	v_sub_f32_e32 v2, v27, v35
	v_exp_f32_e32 v93, v2
	v_sub_f32_e32 v2, v12, v35
	v_exp_f32_e32 v110, v2
	v_sub_f32_e32 v2, v28, v35
	v_exp_f32_e32 v94, v2
	v_sub_f32_e32 v2, v13, v35
	v_exp_f32_e32 v111, v2
	v_sub_f32_e32 v2, v29, v35
	v_exp_f32_e32 v95, v2
	v_sub_f32_e32 v2, v14, v35
	v_exp_f32_e32 v112, v2
	v_sub_f32_e32 v2, v30, v35
	v_exp_f32_e32 v96, v2
	v_sub_f32_e32 v2, v15, v35
	v_exp_f32_e32 v113, v2
	v_sub_f32_e32 v2, v31, v35
	v_exp_f32_e32 v97, v2
	v_sub_f32_e32 v2, v16, v35
	v_exp_f32_e32 v114, v2
	v_sub_f32_e32 v2, v32, v35
	v_exp_f32_e32 v98, v2
	v_sub_f32_e32 v2, v17, v35
	v_sub_f32_e32 v18, v18, v35
	v_sub_f32_e32 v3, v3, v35
	v_sub_f32_e32 v19, v19, v35
	v_sub_f32_e32 v4, v4, v35
	v_sub_f32_e32 v20, v20, v35
	v_sub_f32_e32 v5, v5, v35
	v_sub_f32_e32 v21, v21, v35
	v_sub_f32_e32 v6, v6, v35
	v_sub_f32_e32 v22, v22, v35
	v_sub_f32_e32 v7, v7, v35
	v_sub_f32_e32 v23, v23, v35
	v_sub_f32_e32 v8, v8, v35
	v_sub_f32_e32 v24, v24, v35
	v_sub_f32_e32 v9, v9, v35
	v_sub_f32_e32 v25, v25, v35
	v_exp_f32_e32 v115, v2
	v_sub_f32_e32 v2, v33, v35
	v_exp_f32_e32 v84, v18
	v_exp_f32_e32 v101, v3
	v_exp_f32_e32 v85, v19
	v_exp_f32_e32 v102, v4
	v_exp_f32_e32 v86, v20
	v_exp_f32_e32 v103, v5
	v_exp_f32_e32 v87, v21
	v_exp_f32_e32 v104, v6
	v_exp_f32_e32 v88, v22
	v_exp_f32_e32 v105, v7
	v_exp_f32_e32 v89, v23
	v_exp_f32_e32 v106, v8
	v_exp_f32_e32 v90, v24
	v_exp_f32_e32 v107, v9
	v_exp_f32_e32 v91, v25
	v_exp_f32_e32 v99, v2
	v_sub_f32_e32 v68, v66, v35
	v_mov_b64_e32 v[34:35], v[50:51]
	v_mov_b64_e32 v[18:19], v[50:51]
	v_mov_b64_e32 v[2:3], v[50:51]
	v_mov_b64_e32 v[36:37], v[52:53]
	v_mov_b64_e32 v[38:39], v[54:55]
	v_mov_b64_e32 v[40:41], v[56:57]
	v_mov_b64_e32 v[42:43], v[58:59]
	v_mov_b64_e32 v[44:45], v[60:61]
	v_mov_b64_e32 v[46:47], v[62:63]
	v_mov_b64_e32 v[48:49], v[64:65]
	v_mov_b64_e32 v[20:21], v[52:53]
	v_mov_b64_e32 v[22:23], v[54:55]
	v_mov_b64_e32 v[24:25], v[56:57]
	v_mov_b64_e32 v[26:27], v[58:59]
	v_mov_b64_e32 v[28:29], v[60:61]
	v_mov_b64_e32 v[30:31], v[62:63]
	v_mov_b64_e32 v[32:33], v[64:65]
	v_mov_b64_e32 v[4:5], v[52:53]
	v_mov_b64_e32 v[6:7], v[54:55]
	v_mov_b64_e32 v[8:9], v[56:57]
	v_mov_b64_e32 v[10:11], v[58:59]
	v_mov_b64_e32 v[12:13], v[60:61]
	v_mov_b64_e32 v[14:15], v[62:63]
	v_mov_b64_e32 v[16:17], v[64:65]
	s_branch .LBB0_307

;     ...
;         typedef unsigned u32x2_t __attribute__((ext_vector_type(2)));
;         const int lt = tid - 256;
;         const int key0 = lt >> 5, q16 = lt & 31, cch = q16 >> 1, hlf = q16 & 1;
;         const char* kg = (const char*)(C.cdk + ((size_t)b * PAST * 4 + h) * 128) + (size_t)key0 * 2048 + q16 * 16;
;         const char* vg = (const char*)(C.cdv + ((size_t)b * PAST * 4 + h) * 128) + (size_t)key0 * 2048 + q16 * 16;
;         const int kd0 = (cch >> 3) * 8192 + (cch & 7) * 1024 + ((key0 ^ (cch & 7)) & 63) * 16 + hlf * 8;
;         const int vd0 = S2_V + (cch >> 2) * 4096 + key0 * 64 + (cch & 3) * 16 + hlf * 8;
;         v4u kA[8], vA[8], kB[8], vB[8];
;     ...
;         S2LOAD(kA, vA, 0); S2LOAD(kB, vB, 1);
; template <int KIND>
; __device__ __forceinline__ void attn_queue(const AttnCtx& C, unsigned* head, int nunits, LAS unsigned char* lds) {
;     ...
;         __syncthreads();
;         if (threadIdx.x == 0) slot[0] = __hip_atomic_fetch_add(head, 1u, __ATOMIC_RELAXED, __HIP_MEMORY_SCOPE_AGENT);
;         __syncthreads();
;         const unsigned u = slot[0];
;         if (u >= (unsigned)nunits) break;
.LBB0_656:
	s_or_b64 exec, exec, s[2:3]
	s_waitcnt lgkmcnt(0)
	s_barrier
	ds_read_b32 v2, v1
	s_movk_i32 s2, 0x7f
	s_waitcnt lgkmcnt(0)
	v_cmp_lt_u32_e32 vcc, s2, v2
	s_mov_b64 s[2:3], -1
	s_cbranch_vccnz .LBB0_651
	v_mov_b32_e32 v140, v0
	v_and_b32_e32 v142, 3, v2
	v_readfirstlane_b32 s5, v140
	s_ashr_i32 s4, s5, 6
	s_cmp_lt_i32 s4, 4
	v_and_b32_e32 v208, 31, v140
	v_lshrrev_b32_e32 v207, 2, v2
	s_cselect_b64 s[10:11], -1, 0
	s_cmp_gt_i32 s4, 3
	v_lshlrev_b32_e32 v206, 7, v142
	v_lshlrev_b32_e32 v141, 3, v140
	s_barrier
	s_cbranch_scc0 .LBB0_661
	s_setprio 2
	v_add_u32_e32 v143, 0xffffff00, v140
	v_lshlrev_b32_e32 v3, 21, v207
	v_ashrrev_i32_e32 v2, 5, v143
	v_or_b32_e32 v200, v3, v206
	v_readlane_b32 s60, v253, 7
	v_lshlrev_b64 v[130:131], 2, v[200:201]
	v_readlane_b32 s70, v253, 17
	v_readlane_b32 s71, v253, 18
	v_ashrrev_i32_e32 v3, 31, v2
	v_lshlrev_b64 v[132:133], 11, v[2:3]
	v_lshl_add_u64 v[4:5], s[70:71], 0, v[130:131]
	v_lshl_add_u64 v[4:5], v[4:5], 0, v[132:133]
	v_lshlrev_b32_e32 v200, 4, v208
	v_lshl_add_u64 v[134:135], v[4:5], 0, v[200:201]
	v_readlane_b32 s72, v253, 19
	v_readlane_b32 s73, v253, 20
	v_bfe_u32 v37, v208, 1, 3
	v_add_co_u32_e32 v6, vcc, s1, v134
	v_lshl_add_u64 v[4:5], s[72:73], 0, v[130:131]
	v_bitop3_b32 v3, v2, v37, 63 bitop3:0x6c
	v_addc_co_u32_e32 v7, vcc, 0, v135, vcc
	v_lshl_add_u64 v[34:35], v[4:5], 0, v[132:133]
	v_lshlrev_b32_e32 v66, 4, v3
	v_lshlrev_b32_e32 v146, 6, v2
	global_load_dwordx4 v[2:5], v[134:135], off nt
	global_load_dwordx4 v[10:13], v[6:7], off nt
	v_add_co_u32_e32 v6, vcc, s16, v134
	s_mov_b32 s2, 0x18000
	s_nop 0
	v_addc_co_u32_e32 v7, vcc, 0, v135, vcc
	v_add_co_u32_e32 v14, vcc, s17, v134
	global_load_dwordx4 v[6:9], v[6:7], off nt
	s_nop 0
	v_addc_co_u32_e32 v15, vcc, 0, v135, vcc
	global_load_dwordx4 v[18:21], v[14:15], off nt
	v_add_co_u32_e32 v14, vcc, s18, v134
	v_lshlrev_b32_e32 v38, 3, v208
	s_nop 0
	v_addc_co_u32_e32 v15, vcc, 0, v135, vcc
	v_add_co_u32_e32 v22, vcc, s19, v134
	v_lshl_add_u64 v[136:137], v[34:35], 0, v[200:201]
	s_nop 0
	v_addc_co_u32_e32 v23, vcc, 0, v135, vcc
	v_add_co_u32_e32 v26, vcc, s2, v134
	v_and_b32_e32 v148, 48, v38
	s_nop 0
	v_addc_co_u32_e32 v27, vcc, 0, v135, vcc
	v_add_co_u32_e32 v30, vcc, s20, v134
	global_load_dwordx4 v[14:17], v[14:15], off nt
	s_nop 0
	v_addc_co_u32_e32 v31, vcc, 0, v135, vcc
	v_add_co_u32_e32 v38, vcc, s1, v136
	global_load_dwordx4 v[22:25], v[22:23], off nt
	s_nop 0
	v_addc_co_u32_e32 v39, vcc, 0, v137, vcc
	v_add_co_u32_e32 v42, vcc, s16, v136
	global_load_dwordx4 v[26:29], v[26:27], off nt
	s_nop 0
	v_addc_co_u32_e32 v43, vcc, 0, v137, vcc
	v_add_co_u32_e32 v46, vcc, s17, v136
	global_load_dwordx4 v[30:33], v[30:31], off nt
	s_nop 0
	v_addc_co_u32_e32 v47, vcc, 0, v137, vcc
	v_add_co_u32_e32 v50, vcc, s18, v136
	v_lshlrev_b32_e32 v36, 9, v208
	s_nop 0
	v_addc_co_u32_e32 v51, vcc, 0, v137, vcc
	v_add_co_u32_e32 v54, vcc, s19, v136
	v_and_b32_e32 v34, 0x2000, v36
	s_nop 0
	v_addc_co_u32_e32 v55, vcc, 0, v137, vcc
	v_add_co_u32_e32 v58, vcc, s2, v136
	v_and_b32_e32 v145, 0x3000, v36
	v_lshl_or_b32 v67, v37, 10, v34
	global_load_dwordx4 v[34:37], v[136:137], off nt
	v_addc_co_u32_e32 v59, vcc, 0, v137, vcc
	global_load_dwordx4 v[38:41], v[38:39], off nt
	v_add_co_u32_e32 v62, vcc, s20, v136
	global_load_dwordx4 v[42:45], v[42:43], off nt
	v_readlane_b32 s12, v252, 18
	global_load_dwordx4 v[46:49], v[46:47], off nt
	v_and_b32_e32 v144, 8, v141
	global_load_dwordx4 v[50:53], v[50:51], off nt
	v_addc_co_u32_e32 v63, vcc, 0, v137, vcc
	global_load_dwordx4 v[54:57], v[54:55], off nt
	v_readlane_b32 s15, v252, 21
	global_load_dwordx4 v[58:61], v[58:59], off nt
	v_or3_b32 v147, v67, v66, v144
	global_load_dwordx4 v[62:65], v[62:63], off nt
	v_add_co_u32_e32 v66, vcc, s15, v134
	v_add_u32_e32 v138, 0, v147
	s_nop 0
	v_addc_co_u32_e32 v67, vcc, 0, v135, vcc
	v_add_co_u32_e32 v70, vcc, s21, v134
	global_load_dwordx4 v[66:69], v[66:67], off nt
	s_nop 0
	v_addc_co_u32_e32 v71, vcc, 0, v135, vcc
	global_load_dwordx4 v[74:77], v[70:71], off nt
	v_add_co_u32_e32 v70, vcc, s22, v134
	s_waitcnt vmcnt(17)
	v_cvt_pk_bf16_f32 v2, v2, v3
	v_addc_co_u32_e32 v71, vcc, 0, v135, vcc
	v_add_co_u32_e32 v78, vcc, s23, v134
	global_load_dwordx4 v[70:73], v[70:71], off nt
	s_nop 0
	v_addc_co_u32_e32 v79, vcc, 0, v135, vcc
	v_add_co_u32_e32 v82, vcc, s24, v134
	global_load_dwordx4 v[78:81], v[78:79], off nt
	s_nop 0
	v_addc_co_u32_e32 v83, vcc, 0, v135, vcc
	v_add_co_u32_e32 v86, vcc, s25, v134
	global_load_dwordx4 v[82:85], v[82:83], off nt
	s_nop 0
	v_addc_co_u32_e32 v87, vcc, 0, v135, vcc
	v_add_co_u32_e32 v90, vcc, s26, v134
	global_load_dwordx4 v[86:89], v[86:87], off nt
	s_nop 0
	v_addc_co_u32_e32 v91, vcc, 0, v135, vcc
	v_add_co_u32_e32 v94, vcc, s27, v134
	global_load_dwordx4 v[90:93], v[90:91], off nt
	s_nop 0
	v_addc_co_u32_e32 v95, vcc, 0, v135, vcc
	v_add_co_u32_e32 v98, vcc, s15, v136
	global_load_dwordx4 v[94:97], v[94:95], off nt
	s_nop 0
	v_addc_co_u32_e32 v99, vcc, 0, v137, vcc
	v_add_co_u32_e32 v102, vcc, s21, v136
	global_load_dwordx4 v[98:101], v[98:99], off nt
	s_nop 0
	v_addc_co_u32_e32 v103, vcc, 0, v137, vcc
	v_add_co_u32_e32 v106, vcc, s22, v136
	global_load_dwordx4 v[102:105], v[102:103], off nt
	s_nop 0
	v_addc_co_u32_e32 v107, vcc, 0, v137, vcc
	v_add_co_u32_e32 v110, vcc, s23, v136
	global_load_dwordx4 v[106:109], v[106:107], off nt
	s_nop 0
	v_addc_co_u32_e32 v111, vcc, 0, v137, vcc
	v_add_co_u32_e32 v114, vcc, s24, v136
	global_load_dwordx4 v[110:113], v[110:111], off nt
	s_nop 0
	v_addc_co_u32_e32 v115, vcc, 0, v137, vcc
	v_add_co_u32_e32 v118, vcc, s25, v136
	global_load_dwordx4 v[114:117], v[114:115], off nt
	s_nop 0
	v_addc_co_u32_e32 v119, vcc, 0, v137, vcc
	v_add_co_u32_e32 v122, vcc, s26, v136
	global_load_dwordx4 v[118:121], v[118:119], off nt
	s_nop 0
	v_addc_co_u32_e32 v123, vcc, 0, v137, vcc
	v_add_co_u32_e32 v126, vcc, s27, v136
	global_load_dwordx4 v[122:125], v[122:123], off nt
	s_nop 0
	v_addc_co_u32_e32 v127, vcc, 0, v137, vcc
	global_load_dwordx4 v[126:129], v[126:127], off nt
	v_cvt_pk_bf16_f32 v3, v4, v5
	s_waitcnt vmcnt(30)
;     ...
;         S2LOAD(kA, vA, 0); S2LOAD(kB, vB, 1);
;         S2WRITE(kA, vA, 0); S2LOAD(kA, vA, 2);
;         S2WRITE(kB, vB, 1); S2LOAD(kB, vB, 3);
	v_cvt_pk_bf16_f32 v4, v10, v11
	v_cvt_pk_bf16_f32 v5, v12, v13
	ds_write2_b64 v138, v[2:3], v[4:5] offset1:16
	s_waitcnt vmcnt(29)
	v_cvt_pk_bf16_f32 v2, v6, v7
	v_cvt_pk_bf16_f32 v3, v8, v9
	s_waitcnt vmcnt(28)
	v_cvt_pk_bf16_f32 v4, v18, v19
	v_cvt_pk_bf16_f32 v5, v20, v21
	ds_write2_b64 v138, v[2:3], v[4:5] offset0:32 offset1:48
	s_waitcnt vmcnt(27)
	v_cvt_pk_bf16_f32 v2, v14, v15
	v_cvt_pk_bf16_f32 v3, v16, v17
	s_waitcnt vmcnt(26)
	v_cvt_pk_bf16_f32 v4, v22, v23
	v_cvt_pk_bf16_f32 v5, v24, v25
	ds_write2_b64 v138, v[2:3], v[4:5] offset0:64 offset1:80
	s_waitcnt vmcnt(25)
	v_cvt_pk_bf16_f32 v2, v26, v27
	v_cvt_pk_bf16_f32 v3, v28, v29
	s_waitcnt vmcnt(24)
	v_cvt_pk_bf16_f32 v4, v30, v31
	v_cvt_pk_bf16_f32 v5, v32, v33
	ds_write2_b64 v138, v[2:3], v[4:5] offset0:96 offset1:112
	v_or_b32_e32 v2, v144, v146
	v_add_u32_e32 v2, v2, v145
	v_or_b32_e32 v149, v2, v148
	v_add_u32_e32 v139, 0, v149
	s_waitcnt vmcnt(23)
	v_cvt_pk_bf16_f32 v2, v34, v35
	v_cvt_pk_bf16_f32 v3, v36, v37
	s_waitcnt vmcnt(22)
	v_cvt_pk_bf16_f32 v4, v38, v39
	v_cvt_pk_bf16_f32 v5, v40, v41
	ds_write2st64_b64 v139, v[2:3], v[4:5] offset0:32 offset1:33
	s_waitcnt vmcnt(21)
	v_cvt_pk_bf16_f32 v2, v42, v43
	v_cvt_pk_bf16_f32 v3, v44, v45
	s_waitcnt vmcnt(20)
	v_cvt_pk_bf16_f32 v4, v46, v47
	v_cvt_pk_bf16_f32 v5, v48, v49
	ds_write2st64_b64 v139, v[2:3], v[4:5] offset0:34 offset1:35
	s_waitcnt vmcnt(19)
	v_cvt_pk_bf16_f32 v2, v50, v51
	v_cvt_pk_bf16_f32 v3, v52, v53
	s_waitcnt vmcnt(18)
	v_cvt_pk_bf16_f32 v4, v54, v55
	v_cvt_pk_bf16_f32 v5, v56, v57
	ds_write2st64_b64 v139, v[2:3], v[4:5] offset0:36 offset1:37
	s_waitcnt vmcnt(17)
	v_cvt_pk_bf16_f32 v2, v58, v59
	v_cvt_pk_bf16_f32 v3, v60, v61
	s_waitcnt vmcnt(16)
	v_cvt_pk_bf16_f32 v4, v62, v63
	v_cvt_pk_bf16_f32 v5, v64, v65
	ds_write2st64_b64 v139, v[2:3], v[4:5] offset0:38 offset1:39
	v_add_co_u32_e32 v2, vcc, s28, v134
	s_waitcnt vmcnt(15)
	v_cvt_pk_bf16_f32 v66, v66, v67
	v_addc_co_u32_e32 v3, vcc, 0, v135, vcc
	v_add_co_u32_e32 v6, vcc, s29, v134
	global_load_dwordx4 v[2:5], v[2:3], off nt
	s_nop 0
	v_addc_co_u32_e32 v7, vcc, 0, v135, vcc
	global_load_dwordx4 v[22:25], v[6:7], off nt
	v_add_co_u32_e32 v6, vcc, s30, v134
	v_cvt_pk_bf16_f32 v67, v68, v69
	s_nop 0
	v_addc_co_u32_e32 v7, vcc, 0, v135, vcc
	v_add_co_u32_e32 v10, vcc, s31, v134
	global_load_dwordx4 v[6:9], v[6:7], off nt
	s_nop 0
	v_addc_co_u32_e32 v11, vcc, 0, v135, vcc
	global_load_dwordx4 v[26:29], v[10:11], off nt
	v_add_co_u32_e32 v10, vcc, s33, v134
	s_waitcnt vmcnt(18)
	v_cvt_pk_bf16_f32 v68, v74, v75
	v_addc_co_u32_e32 v11, vcc, 0, v135, vcc
	v_add_co_u32_e32 v14, vcc, s34, v134
	global_load_dwordx4 v[10:13], v[10:11], off nt
	s_nop 0
	v_addc_co_u32_e32 v15, vcc, 0, v135, vcc
	global_load_dwordx4 v[30:33], v[14:15], off nt
	v_add_co_u32_e32 v14, vcc, s35, v134
	v_cvt_pk_bf16_f32 v69, v76, v77
	s_nop 0
	v_addc_co_u32_e32 v15, vcc, 0, v135, vcc
	v_add_co_u32_e32 v18, vcc, s36, v134
	v_add_u32_e32 v74, 0x8000, v138
	s_nop 0
	v_addc_co_u32_e32 v19, vcc, 0, v135, vcc
	v_add_co_u32_e32 v34, vcc, s28, v136
	ds_write2_b64 v74, v[66:67], v[68:69] offset1:16
	s_nop 0
	v_addc_co_u32_e32 v35, vcc, 0, v137, vcc
	global_load_dwordx4 v[42:45], v[34:35], off nt
	v_add_co_u32_e32 v34, vcc, s29, v136
	s_waitcnt vmcnt(20)
	v_cvt_pk_bf16_f32 v66, v70, v71
	v_addc_co_u32_e32 v35, vcc, 0, v137, vcc
	global_load_dwordx4 v[58:61], v[34:35], off nt
	v_add_co_u32_e32 v34, vcc, s30, v136
	v_cvt_pk_bf16_f32 v67, v72, v73
	s_nop 0
	v_addc_co_u32_e32 v35, vcc, 0, v137, vcc
	global_load_dwordx4 v[38:41], v[34:35], off nt
	v_add_co_u32_e32 v34, vcc, s31, v136
	s_waitcnt vmcnt(21)
	v_cvt_pk_bf16_f32 v68, v78, v79
	v_addc_co_u32_e32 v35, vcc, 0, v137, vcc
	global_load_dwordx4 v[54:57], v[34:35], off nt
	v_add_co_u32_e32 v34, vcc, s33, v136
	v_cvt_pk_bf16_f32 v69, v80, v81
	s_nop 0
	v_addc_co_u32_e32 v35, vcc, 0, v137, vcc
	global_load_dwordx4 v[46:49], v[34:35], off nt
	v_add_co_u32_e32 v34, vcc, s34, v136
	ds_write2_b64 v74, v[66:67], v[68:69] offset0:32 offset1:48
	s_waitcnt vmcnt(22)
	v_cvt_pk_bf16_f32 v66, v82, v83
	v_cvt_pk_bf16_f32 v67, v84, v85
	s_waitcnt vmcnt(21)
	v_cvt_pk_bf16_f32 v68, v86, v87
	v_cvt_pk_bf16_f32 v69, v88, v89
	v_addc_co_u32_e32 v35, vcc, 0, v137, vcc
	ds_write2_b64 v74, v[66:67], v[68:69] offset0:64 offset1:80
	s_waitcnt vmcnt(20)
	v_cvt_pk_bf16_f32 v66, v90, v91
	v_cvt_pk_bf16_f32 v67, v92, v93
	s_waitcnt vmcnt(19)
; #define S2BAR() asm volatile("s_waitcnt lgkmcnt(0)\n\ts_barrier" ::: "memory")
;     ...
;         S2LOAD(kA, vA, 0); S2LOAD(kB, vB, 1);
;         S2WRITE(kA, vA, 0); S2LOAD(kA, vA, 2);
;         S2WRITE(kB, vB, 1); S2LOAD(kB, vB, 3);
;         S2BAR();
;         for (int i = 0; i < 60; i += 2) {
;             S2WRITE(kA, vA, i + 2); S2LOAD(kA, vA, i + 4); S2BAR();
;             S2WRITE(kB, vB, i + 3); S2LOAD(kB, vB, i + 5); S2BAR();
;         }
	v_cvt_pk_bf16_f32 v68, v94, v95
	v_cvt_pk_bf16_f32 v69, v96, v97
	global_load_dwordx4 v[62:65], v[34:35], off nt
	v_add_co_u32_e32 v34, vcc, s35, v136
	ds_write2_b64 v74, v[66:67], v[68:69] offset0:96 offset1:112
	s_waitcnt vmcnt(19)
	v_cvt_pk_bf16_f32 v66, v98, v99
	v_cvt_pk_bf16_f32 v67, v100, v101
	s_waitcnt vmcnt(18)
	v_cvt_pk_bf16_f32 v68, v102, v103
	v_cvt_pk_bf16_f32 v69, v104, v105
	v_addc_co_u32_e32 v35, vcc, 0, v137, vcc
	ds_write2st64_b64 v139, v[66:67], v[68:69] offset0:96 offset1:97
	s_waitcnt vmcnt(17)
	v_cvt_pk_bf16_f32 v66, v106, v107
	v_cvt_pk_bf16_f32 v67, v108, v109
	s_waitcnt vmcnt(16)
	v_cvt_pk_bf16_f32 v68, v110, v111
	v_cvt_pk_bf16_f32 v69, v112, v113
	global_load_dwordx4 v[50:53], v[34:35], off nt
	v_add_co_u32_e32 v34, vcc, s36, v136
	ds_write2st64_b64 v139, v[66:67], v[68:69] offset0:98 offset1:99
	s_waitcnt vmcnt(16)
	v_cvt_pk_bf16_f32 v66, v114, v115
	v_cvt_pk_bf16_f32 v67, v116, v117
	s_waitcnt vmcnt(15)
	v_cvt_pk_bf16_f32 v68, v118, v119
	v_cvt_pk_bf16_f32 v69, v120, v121
	v_addc_co_u32_e32 v35, vcc, 0, v137, vcc
	ds_write2st64_b64 v139, v[66:67], v[68:69] offset0:100 offset1:101
	s_waitcnt vmcnt(14)
	v_cvt_pk_bf16_f32 v66, v122, v123
	v_cvt_pk_bf16_f32 v67, v124, v125
	s_waitcnt vmcnt(13)
	v_cvt_pk_bf16_f32 v68, v126, v127
	v_cvt_pk_bf16_f32 v69, v128, v129
	ds_write2st64_b64 v139, v[66:67], v[68:69] offset0:102 offset1:103
	v_add_co_u32_e32 v66, vcc, s37, v134
	s_mov_b32 s3, 0x78000
	s_nop 0
	v_addc_co_u32_e32 v67, vcc, 0, v135, vcc
	global_load_dwordx4 v[74:77], v[66:67], off nt
	v_add_co_u32_e32 v66, vcc, s38, v134
	global_load_dwordx4 v[14:17], v[14:15], off nt
	s_nop 0
	v_addc_co_u32_e32 v67, vcc, 0, v135, vcc
	global_load_dwordx4 v[86:89], v[66:67], off nt
	v_add_co_u32_e32 v66, vcc, s39, v134
	global_load_dwordx4 v[18:21], v[18:19], off nt
	s_nop 0
	v_addc_co_u32_e32 v67, vcc, 0, v135, vcc
	global_load_dwordx4 v[70:73], v[66:67], off nt
	v_add_co_u32_e32 v66, vcc, s40, v134
	global_load_dwordx4 v[34:37], v[34:35], off nt
	s_nop 0
	v_addc_co_u32_e32 v67, vcc, 0, v135, vcc
	global_load_dwordx4 v[82:85], v[66:67], off nt
	v_add_co_u32_e32 v66, vcc, s41, v134
	v_or_b32_e32 v132, v132, v200
	s_nop 0
	v_addc_co_u32_e32 v67, vcc, 0, v135, vcc
	v_add_co_u32_e32 v78, vcc, s42, v134
	global_load_dwordx4 v[66:69], v[66:67], off nt
	s_nop 0
	v_addc_co_u32_e32 v79, vcc, 0, v135, vcc
	v_add_co_u32_e32 v90, vcc, s3, v134
	s_mov_b32 s3, 0x7c000
	s_nop 0
	v_addc_co_u32_e32 v91, vcc, 0, v135, vcc
	v_add_co_u32_e32 v94, vcc, s3, v134
	global_load_dwordx4 v[90:93], v[90:91], off nt
	s_nop 0
	v_addc_co_u32_e32 v95, vcc, 0, v135, vcc
	global_load_dwordx4 v[98:101], v[94:95], off nt
	v_add_co_u32_e32 v94, vcc, s37, v136
	global_load_dwordx4 v[78:81], v[78:79], off nt
	s_nop 0
	v_addc_co_u32_e32 v95, vcc, 0, v137, vcc
	v_add_co_u32_e32 v102, vcc, s38, v136
	global_load_dwordx4 v[94:97], v[94:95], off nt
	s_nop 0
	v_addc_co_u32_e32 v103, vcc, 0, v137, vcc
	global_load_dwordx4 v[106:109], v[102:103], off nt
	v_add_co_u32_e32 v102, vcc, s39, v136
	v_lshl_add_u64 v[134:135], s[70:71], 0, v[132:133]
	s_nop 0
	v_addc_co_u32_e32 v103, vcc, 0, v137, vcc
	v_add_co_u32_e32 v110, vcc, s40, v136
	global_load_dwordx4 v[102:105], v[102:103], off nt
	s_nop 0
	v_addc_co_u32_e32 v111, vcc, 0, v137, vcc
	v_add_co_u32_e32 v114, vcc, s41, v136
	global_load_dwordx4 v[110:113], v[110:111], off nt
	s_nop 0
	v_addc_co_u32_e32 v115, vcc, 0, v137, vcc
	v_add_co_u32_e32 v118, vcc, s42, v136
	global_load_dwordx4 v[114:117], v[114:115], off nt
	s_nop 0
	v_addc_co_u32_e32 v119, vcc, 0, v137, vcc
	v_add_co_u32_e32 v122, vcc, 0x78000, v136
	global_load_dwordx4 v[118:121], v[118:119], off nt
	s_nop 0
	v_addc_co_u32_e32 v123, vcc, 0, v137, vcc
	v_add_co_u32_e32 v126, vcc, 0x7c000, v136
	global_load_dwordx4 v[122:125], v[122:123], off nt
	s_nop 0
	v_addc_co_u32_e32 v127, vcc, 0, v137, vcc
	global_load_dwordx4 v[126:129], v[126:127], off nt
	s_waitcnt lgkmcnt(0)
	s_barrier
	v_lshl_add_u64 v[132:133], s[72:73], 0, v[132:133]
	s_mov_b32 s3, -2
	v_readlane_b32 s61, v253, 8
	v_readlane_b32 s62, v253, 9
	v_readlane_b32 s63, v253, 10
	v_readlane_b32 s64, v253, 11
	v_readlane_b32 s65, v253, 12
	v_readlane_b32 s66, v253, 13
	v_readlane_b32 s67, v253, 14
	v_readlane_b32 s68, v253, 15
	v_readlane_b32 s69, v253, 16
	v_readlane_b32 s74, v253, 21
	v_readlane_b32 s75, v253, 22
	v_readlane_b32 s13, v252, 19
	v_readlane_b32 s14, v252, 20
